# speedup vs baseline: 1.0205x; 1.0205x over previous
; #define STAGE_A(Poff, off, hrow) do { const unsigned _s = (off) + (unsigned)(hrow) * lda2;                                \
;     GLDS(ldsw + (Poff), offA, srdA, _s); GLDS(ldsw + (Poff) + 8192, offA, srdA, _s + lda128); } while (0)
; #define STAGE_B(Poff, off, hrow) do { const unsigned _s = (off) + (unsigned)(hrow) * ldb2;                                \
;     GLDS(ldsw + (Poff), offB, srdB, _s); GLDS(ldsw + (Poff) + 8192, offB, srdB, _s + ldb128); } while (0)
; #define LDA(dst, b, h) _Pragma("unroll") for (int m = 0; m < 4; ++m) _Pragma("unroll") for (int k = 0; k < 2; ++k) \
;     dst[m][k] = *reinterpret_cast<const bf16x8*>((const char*)SA(b, h) + aoff + (m * 2 + k) * 1024)
; #define LDB(dst, b, h) _Pragma("unroll") for (int n = 0; n < 2; ++n) _Pragma("unroll") for (int k = 0; k < 2; ++k) \
;     dst[n][k] = *reinterpret_cast<const bf16x8*>((const char*)SB(b, h) + boff + (n * 2 + k) * 1024)
; #define WAIT_V(n) asm volatile("s_waitcnt vmcnt(" #n ")" ::: "memory")
; #define WAIT_L(n) asm volatile("s_waitcnt lgkmcnt(" #n ")" ::: "memory")
; #define BAR __builtin_amdgcn_s_barrier()
; #define SCHED __builtin_amdgcn_sched_barrier(0)
; __device__ __forceinline__ void gemm_phase(const int tid_, const GemmArgs& ga, u16* shm) {
;     ...
;       for (int t = 0; t < nt; t += 2) {
;         const bool last = t + 2 >= nt;
;         const unsigned pA1 = gA + (unsigned)(t + 1) * 128u;
;         const unsigned pA2 = last ? gAn : gA + (unsigned)(t + 2) * 128u;
;         const unsigned pB2 = last ? gBn : gB + (unsigned)(t + 2) * 128u;
;         LDB(B0, 0, 0); SCHED; LDA(At, 0, 0); STAGE_A(SAO(1, 1), pA1, HALF);
;         WAIT_L(8); BAR; WAIT_L(0); MMA(0, 0, At, B0); BAR; SCHED;
;         LDB(B1, 0, 1); STAGE_B(SBO(0, 0), pB2, 0);
;         BAR; WAIT_L(0); MMA(0, 1, At, B1); BAR;
;         LDA(At, 0, 1); STAGE_A(SAO(0, 0), pA2, 0);
;         BAR; WAIT_L(0); MMA(1, 0, At, B0); BAR; SCHED;
;         STAGE_B(SBO(0, 1), pB2, HALF);
;         WAIT_V(6); BAR; MMA(1, 1, At, B1); BAR;
.LBB0_316:
	v_add_u32_e32 v96, 0x10000, v224
	s_mov_b32 s6, s78
	ds_read_b128 v[132:135], v96
	ds_read_b128 v[136:139], v96 offset:1024
	ds_read_b128 v[140:143], v96 offset:2048
	ds_read_b128 v[144:147], v96 offset:3072
	s_add_i32 s78, s78, 2
	s_lshl_b32 s6, s6, 7
	s_lshl_b32 s7, s78, 7
	s_add_i32 s10, s79, s6
	s_add_i32 s8, s7, s54
	s_add_i32 s9, s7, s1
	s_add_i32 s11, s10, s62
	s_cmp_ge_u32 s78, s67
	s_cselect_b64 s[28:29], -1, 0
	s_and_b64 s[6:7], s[28:29], exec
	s_cselect_b32 s6, s19, s8
	ds_read_b128 v[152:155], v225
	ds_read_b128 v[156:159], v225 offset:1024
	ds_read_b128 v[160:163], v225 offset:2048
	ds_read_b128 v[164:167], v225 offset:3072
	ds_read_b128 v[168:171], v225 offset:4096
	ds_read_b128 v[172:175], v225 offset:5120
	ds_read_b128 v[176:179], v225 offset:6144
	ds_read_b128 v[180:183], v225 offset:7168
	s_mov_b32 m0, s66
	s_nop 0
	buffer_load_dwordx4 v222, s[48:51], s10 offen lds
	s_nop 0
	s_mov_b32 m0, s18
	s_nop 0
	buffer_load_dwordx4 v222, s[48:51], s11 offen lds
	v_add_u32_e32 v96, 0x14000, v224
	ds_read_b128 v[184:187], v96
	ds_read_b128 v[188:191], v96 offset:1024
	ds_read_b128 v[192:195], v96 offset:2048
	ds_read_b128 v[196:199], v96 offset:3072
	s_waitcnt lgkmcnt(0)
	s_waitcnt vmcnt(8)
	s_barrier
	s_setprio 1
	v_mfma_f32_16x16x32_bf16 v[128:131], v[132:135], v[152:155], v[128:131]
	v_mfma_f32_16x16x32_bf16 v[124:127], v[140:143], v[152:155], v[124:127]
	v_mfma_f32_16x16x32_bf16 v[120:123], v[132:135], v[160:163], v[120:123]
	v_mfma_f32_16x16x32_bf16 v[116:119], v[140:143], v[160:163], v[116:119]
	v_mfma_f32_16x16x32_bf16 v[112:115], v[132:135], v[168:171], v[112:115]
	v_mfma_f32_16x16x32_bf16 v[108:111], v[140:143], v[168:171], v[108:111]
	v_mfma_f32_16x16x32_bf16 v[104:107], v[132:135], v[176:179], v[104:107]
	v_mfma_f32_16x16x32_bf16 v[98:101], v[140:143], v[176:179], v[100:103]
	v_mfma_f32_16x16x32_bf16 v[128:131], v[136:139], v[156:159], v[128:131]
	v_mfma_f32_16x16x32_bf16 v[124:127], v[144:147], v[156:159], v[124:127]
	v_mfma_f32_16x16x32_bf16 v[120:123], v[136:139], v[164:167], v[120:123]
	v_mfma_f32_16x16x32_bf16 v[116:119], v[144:147], v[164:167], v[116:119]
	v_mfma_f32_16x16x32_bf16 v[112:115], v[136:139], v[172:175], v[112:115]
	v_mfma_f32_16x16x32_bf16 v[108:111], v[144:147], v[172:175], v[108:111]
	v_mfma_f32_16x16x32_bf16 v[102:105], v[136:139], v[180:183], v[104:107]
	v_mfma_f32_16x16x32_bf16 v[98:101], v[144:147], v[180:183], v[98:101]
	v_mfma_f32_16x16x32_bf16 v[92:95], v[184:187], v[152:155], v[92:95]
	v_mfma_f32_16x16x32_bf16 v[88:91], v[192:195], v[152:155], v[88:91]
	v_mfma_f32_16x16x32_bf16 v[84:87], v[184:187], v[160:163], v[84:87]
	v_mfma_f32_16x16x32_bf16 v[80:83], v[192:195], v[160:163], v[80:83]
	v_mfma_f32_16x16x32_bf16 v[76:79], v[184:187], v[168:171], v[76:79]
	v_mfma_f32_16x16x32_bf16 v[72:75], v[192:195], v[168:171], v[72:75]
	v_mfma_f32_16x16x32_bf16 v[68:71], v[184:187], v[176:179], v[68:71]
	v_mfma_f32_16x16x32_bf16 v[64:67], v[192:195], v[176:179], v[64:67]
	v_mfma_f32_16x16x32_bf16 v[92:95], v[188:191], v[156:159], v[92:95]
	v_mfma_f32_16x16x32_bf16 v[88:91], v[196:199], v[156:159], v[88:91]
	v_mfma_f32_16x16x32_bf16 v[84:87], v[188:191], v[164:167], v[84:87]
	v_mfma_f32_16x16x32_bf16 v[80:83], v[196:199], v[164:167], v[80:83]
	v_mfma_f32_16x16x32_bf16 v[76:79], v[188:191], v[172:175], v[76:79]
	v_mfma_f32_16x16x32_bf16 v[72:75], v[196:199], v[172:175], v[72:75]
	v_mfma_f32_16x16x32_bf16 v[68:71], v[188:191], v[180:183], v[68:71]
	v_mfma_f32_16x16x32_bf16 v[64:67], v[196:199], v[180:183], v[64:67]
	s_setprio 0
	s_barrier
	ds_read_b128 v[152:155], v225 offset:16384
	ds_read_b128 v[156:159], v225 offset:17408
	ds_read_b128 v[160:163], v225 offset:18432
	ds_read_b128 v[164:167], v225 offset:19456
	ds_read_b128 v[168:171], v225 offset:20480
	ds_read_b128 v[172:175], v225 offset:21504
	ds_read_b128 v[176:179], v225 offset:22528
	ds_read_b128 v[180:183], v225 offset:23552
	s_cselect_b32 s7, s64, s9
	s_mov_b32 m0, s65
	s_nop 0
	buffer_load_dwordx4 v223, s[44:47], s7 offen lds
	s_add_i32 s8, s7, s63
	s_mov_b32 m0, s72
	s_nop 0
	buffer_load_dwordx4 v223, s[44:47], s8 offen lds
	s_mov_b32 m0, s55
	s_nop 0
	buffer_load_dwordx4 v222, s[48:51], s6 offen lds
	s_add_i32 s9, s6, s62
	s_mov_b32 m0, s73
	s_nop 0
	buffer_load_dwordx4 v222, s[48:51], s9 offen lds
	s_add_i32 s8, s8, s63
	s_mov_b32 m0, s52
	s_nop 0
	buffer_load_dwordx4 v223, s[44:47], s8 offen lds
	s_add_i32 s8, s8, s63
	s_mov_b32 m0, s58
	s_nop 0
	buffer_load_dwordx4 v223, s[44:47], s8 offen lds
	s_waitcnt lgkmcnt(0)
	s_waitcnt vmcnt(8)
	s_barrier
; #define STAGE_A(Poff, off, hrow) do { const unsigned _s = (off) + (unsigned)(hrow) * lda2;                                \
;     GLDS(ldsw + (Poff), offA, srdA, _s); GLDS(ldsw + (Poff) + 8192, offA, srdA, _s + lda128); } while (0)
; #define STAGE_B(Poff, off, hrow) do { const unsigned _s = (off) + (unsigned)(hrow) * ldb2;                                \
;     GLDS(ldsw + (Poff), offB, srdB, _s); GLDS(ldsw + (Poff) + 8192, offB, srdB, _s + ldb128); } while (0)
; #define LDA(dst, b, h) _Pragma("unroll") for (int m = 0; m < 4; ++m) _Pragma("unroll") for (int k = 0; k < 2; ++k) \
;     dst[m][k] = *reinterpret_cast<const bf16x8*>((const char*)SA(b, h) + aoff + (m * 2 + k) * 1024)
; #define LDB(dst, b, h) _Pragma("unroll") for (int n = 0; n < 2; ++n) _Pragma("unroll") for (int k = 0; k < 2; ++k) \
;     dst[n][k] = *reinterpret_cast<const bf16x8*>((const char*)SB(b, h) + boff + (n * 2 + k) * 1024)
; #define WAIT_V(n) asm volatile("s_waitcnt vmcnt(" #n ")" ::: "memory")
; #define WAIT_L(n) asm volatile("s_waitcnt lgkmcnt(" #n ")" ::: "memory")
; #define BAR __builtin_amdgcn_s_barrier()
; #define SCHED __builtin_amdgcn_sched_barrier(0)
; __device__ __forceinline__ void gemm_phase(const int tid_, const GemmArgs& ga, u16* shm) {
;     ...
;         LDA(At, 0, 1); STAGE_A(SAO(0, 0), pA2, 0);
;         BAR; WAIT_L(0); MMA(1, 0, At, B0); BAR; SCHED;
;         STAGE_B(SBO(0, 1), pB2, HALF);
;         WAIT_V(6); BAR; MMA(1, 1, At, B1); BAR;
;         LDB(B0, 1, 0); SCHED; LDA(At, 1, 0); STAGE_A(SAO(0, 1), pA2, HALF);
;         WAIT_L(8); BAR; WAIT_L(0); MMA(0, 0, At, B0); BAR; SCHED;
;         LDB(B1, 1, 1); STAGE_B(SBO(1, 0), pB2 + 128, 0);
;         BAR; WAIT_L(0); MMA(0, 1, At, B1); BAR;
;         LDA(At, 1, 1); STAGE_A(SAO(1, 0), pA2 + 128, 0);
;         BAR; WAIT_L(0); MMA(1, 0, At, B0); BAR; SCHED;
	s_setprio 1
	v_mfma_f32_16x16x32_bf16 v[60:63], v[132:135], v[152:155], v[60:63]
	v_mfma_f32_16x16x32_bf16 v[56:59], v[140:143], v[152:155], v[56:59]
	v_mfma_f32_16x16x32_bf16 v[52:55], v[132:135], v[160:163], v[52:55]
	v_mfma_f32_16x16x32_bf16 v[48:51], v[140:143], v[160:163], v[48:51]
	v_mfma_f32_16x16x32_bf16 v[44:47], v[132:135], v[168:171], v[44:47]
	v_mfma_f32_16x16x32_bf16 v[40:43], v[140:143], v[168:171], v[40:43]
	v_mfma_f32_16x16x32_bf16 v[36:39], v[132:135], v[176:179], v[36:39]
	v_mfma_f32_16x16x32_bf16 v[32:35], v[140:143], v[176:179], v[32:35]
	v_mfma_f32_16x16x32_bf16 v[60:63], v[136:139], v[156:159], v[60:63]
	v_mfma_f32_16x16x32_bf16 v[56:59], v[144:147], v[156:159], v[56:59]
	v_mfma_f32_16x16x32_bf16 v[52:55], v[136:139], v[164:167], v[52:55]
	v_mfma_f32_16x16x32_bf16 v[48:51], v[144:147], v[164:167], v[48:51]
	v_mfma_f32_16x16x32_bf16 v[44:47], v[136:139], v[172:175], v[44:47]
	v_mfma_f32_16x16x32_bf16 v[40:43], v[144:147], v[172:175], v[40:43]
	v_mfma_f32_16x16x32_bf16 v[36:39], v[136:139], v[180:183], v[36:39]
	v_mfma_f32_16x16x32_bf16 v[32:35], v[144:147], v[180:183], v[32:35]
	v_mfma_f32_16x16x32_bf16 v[28:31], v[184:187], v[152:155], v[28:31]
	v_mfma_f32_16x16x32_bf16 v[24:27], v[192:195], v[152:155], v[24:27]
	v_mfma_f32_16x16x32_bf16 v[20:23], v[184:187], v[160:163], v[20:23]
	v_mfma_f32_16x16x32_bf16 v[16:19], v[192:195], v[160:163], v[16:19]
	v_mfma_f32_16x16x32_bf16 v[12:15], v[184:187], v[168:171], v[12:15]
	v_mfma_f32_16x16x32_bf16 v[8:11], v[192:195], v[168:171], v[8:11]
	v_mfma_f32_16x16x32_bf16 v[4:7], v[184:187], v[176:179], v[4:7]
	v_mfma_f32_16x16x32_bf16 v[0:3], v[192:195], v[176:179], v[0:3]
	v_mfma_f32_16x16x32_bf16 v[28:31], v[188:191], v[156:159], v[28:31]
	v_mfma_f32_16x16x32_bf16 v[24:27], v[196:199], v[156:159], v[24:27]
	v_mfma_f32_16x16x32_bf16 v[20:23], v[188:191], v[164:167], v[20:23]
	v_mfma_f32_16x16x32_bf16 v[16:19], v[196:199], v[164:167], v[16:19]
	v_mfma_f32_16x16x32_bf16 v[12:15], v[188:191], v[172:175], v[12:15]
	v_mfma_f32_16x16x32_bf16 v[8:11], v[196:199], v[172:175], v[8:11]
	v_mfma_f32_16x16x32_bf16 v[4:7], v[188:191], v[180:183], v[4:7]
	v_mfma_f32_16x16x32_bf16 v[0:3], v[196:199], v[180:183], v[0:3]
	s_setprio 0
	s_barrier
	v_add_u32_e32 v96, 0x18000, v224
	ds_read_b128 v[132:135], v96
	ds_read_b128 v[136:139], v96 offset:1024
	ds_read_b128 v[140:143], v96 offset:2048
	ds_read_b128 v[144:147], v96 offset:3072
	ds_read_b128 v[152:155], v225 offset:32768
	ds_read_b128 v[156:159], v225 offset:33792
	ds_read_b128 v[160:163], v225 offset:34816
	ds_read_b128 v[164:167], v225 offset:35840
	ds_read_b128 v[168:171], v225 offset:36864
	ds_read_b128 v[172:175], v225 offset:37888
	ds_read_b128 v[176:179], v225 offset:38912
	ds_read_b128 v[180:183], v225 offset:39936
	v_add_u32_e32 v96, 0x1c000, v224
	ds_read_b128 v[184:187], v96
	ds_read_b128 v[188:191], v96 offset:1024
	ds_read_b128 v[192:195], v96 offset:2048
	ds_read_b128 v[196:199], v96 offset:3072
	s_add_i32 s8, s9, s62
	s_mov_b32 m0, s59
	s_nop 0
	buffer_load_dwordx4 v222, s[48:51], s8 offen lds
	s_add_i32 s8, s8, s62
	s_mov_b32 m0, s2
	s_nop 0
	buffer_load_dwordx4 v222, s[48:51], s8 offen lds
	s_waitcnt lgkmcnt(0)
	s_waitcnt vmcnt(8)
	s_barrier
	s_setprio 1
	v_mfma_f32_16x16x32_bf16 v[128:131], v[132:135], v[152:155], v[128:131]
	v_mfma_f32_16x16x32_bf16 v[124:127], v[140:143], v[152:155], v[124:127]
	v_mfma_f32_16x16x32_bf16 v[120:123], v[132:135], v[160:163], v[120:123]
	v_mfma_f32_16x16x32_bf16 v[116:119], v[140:143], v[160:163], v[116:119]
	v_mfma_f32_16x16x32_bf16 v[112:115], v[132:135], v[168:171], v[112:115]
	v_mfma_f32_16x16x32_bf16 v[106:109], v[140:143], v[168:171], v[108:111]
	v_mfma_f32_16x16x32_bf16 v[102:105], v[132:135], v[176:179], v[102:105]
	v_mfma_f32_16x16x32_bf16 v[98:101], v[140:143], v[176:179], v[98:101]
	v_mfma_f32_16x16x32_bf16 v[128:131], v[136:139], v[156:159], v[128:131]
	v_mfma_f32_16x16x32_bf16 v[124:127], v[144:147], v[156:159], v[124:127]
	v_mfma_f32_16x16x32_bf16 v[120:123], v[136:139], v[164:167], v[120:123]
	v_mfma_f32_16x16x32_bf16 v[116:119], v[144:147], v[164:167], v[116:119]
	v_mfma_f32_16x16x32_bf16 v[112:115], v[136:139], v[172:175], v[112:115]
	v_mfma_f32_16x16x32_bf16 v[108:111], v[144:147], v[172:175], v[106:109]
	v_mfma_f32_16x16x32_bf16 v[104:107], v[136:139], v[180:183], v[102:105]
	v_mfma_f32_16x16x32_bf16 v[100:103], v[144:147], v[180:183], v[98:101]
	v_mfma_f32_16x16x32_bf16 v[92:95], v[184:187], v[152:155], v[92:95]
	v_mfma_f32_16x16x32_bf16 v[88:91], v[192:195], v[152:155], v[88:91]
	v_mfma_f32_16x16x32_bf16 v[84:87], v[184:187], v[160:163], v[84:87]
	v_mfma_f32_16x16x32_bf16 v[80:83], v[192:195], v[160:163], v[80:83]
	v_mfma_f32_16x16x32_bf16 v[76:79], v[184:187], v[168:171], v[76:79]
	v_mfma_f32_16x16x32_bf16 v[72:75], v[192:195], v[168:171], v[72:75]
	v_mfma_f32_16x16x32_bf16 v[68:71], v[184:187], v[176:179], v[68:71]
	v_mfma_f32_16x16x32_bf16 v[64:67], v[192:195], v[176:179], v[64:67]
	v_mfma_f32_16x16x32_bf16 v[92:95], v[188:191], v[156:159], v[92:95]
	v_mfma_f32_16x16x32_bf16 v[88:91], v[196:199], v[156:159], v[88:91]
	v_mfma_f32_16x16x32_bf16 v[84:87], v[188:191], v[164:167], v[84:87]
	v_mfma_f32_16x16x32_bf16 v[80:83], v[196:199], v[164:167], v[80:83]
	v_mfma_f32_16x16x32_bf16 v[76:79], v[188:191], v[172:175], v[76:79]
	v_mfma_f32_16x16x32_bf16 v[72:75], v[196:199], v[172:175], v[72:75]
	v_mfma_f32_16x16x32_bf16 v[68:71], v[188:191], v[180:183], v[68:71]
	v_mfma_f32_16x16x32_bf16 v[64:67], v[196:199], v[180:183], v[64:67]
	s_setprio 0
	s_barrier
; #define STAGE_A(Poff, off, hrow) do { const unsigned _s = (off) + (unsigned)(hrow) * lda2;                                \
;     GLDS(ldsw + (Poff), offA, srdA, _s); GLDS(ldsw + (Poff) + 8192, offA, srdA, _s + lda128); } while (0)
; #define STAGE_B(Poff, off, hrow) do { const unsigned _s = (off) + (unsigned)(hrow) * ldb2;                                \
;     GLDS(ldsw + (Poff), offB, srdB, _s); GLDS(ldsw + (Poff) + 8192, offB, srdB, _s + ldb128); } while (0)
; #define LDA(dst, b, h) _Pragma("unroll") for (int m = 0; m < 4; ++m) _Pragma("unroll") for (int k = 0; k < 2; ++k) \
;     dst[m][k] = *reinterpret_cast<const bf16x8*>((const char*)SA(b, h) + aoff + (m * 2 + k) * 1024)
; #define LDB(dst, b, h) _Pragma("unroll") for (int n = 0; n < 2; ++n) _Pragma("unroll") for (int k = 0; k < 2; ++k) \
;     dst[n][k] = *reinterpret_cast<const bf16x8*>((const char*)SB(b, h) + boff + (n * 2 + k) * 1024)
; #define WAIT_V(n) asm volatile("s_waitcnt vmcnt(" #n ")" ::: "memory")
; #define WAIT_L(n) asm volatile("s_waitcnt lgkmcnt(" #n ")" ::: "memory")
; #define BAR __builtin_amdgcn_s_barrier()
; #define SCHED __builtin_amdgcn_sched_barrier(0)
; __device__ __forceinline__ void gemm_phase(const int tid_, const GemmArgs& ga, u16* shm) {
;     ...
;         LDB(B1, 1, 1); STAGE_B(SBO(1, 0), pB2 + 128, 0);
;         BAR; WAIT_L(0); MMA(0, 1, At, B1); BAR;
;         LDA(At, 1, 1); STAGE_A(SAO(1, 0), pA2 + 128, 0);
;         BAR; WAIT_L(0); MMA(1, 0, At, B0); BAR; SCHED;
;         STAGE_B(SBO(1, 1), pB2 + 128, HALF);
;         WAIT_V(6); BAR; MMA(1, 1, At, B1);
	ds_read_b128 v[152:155], v225 offset:49152
	ds_read_b128 v[156:159], v225 offset:50176
	ds_read_b128 v[160:163], v225 offset:51200
	ds_read_b128 v[164:167], v225 offset:52224
	ds_read_b128 v[168:171], v225 offset:53248
	ds_read_b128 v[172:175], v225 offset:54272
	ds_read_b128 v[176:179], v225 offset:55296
	ds_read_b128 v[180:183], v225 offset:56320
	s_addk_i32 s7, 0x80
	s_mov_b32 m0, s98
	s_nop 0
	buffer_load_dwordx4 v223, s[44:47], s7 offen lds
	s_add_i32 s7, s7, s63
	s_mov_b32 m0, s99
	s_nop 0
	buffer_load_dwordx4 v223, s[44:47], s7 offen lds
	s_addk_i32 s6, 0x80
	s_mov_b32 m0, s68
	s_nop 0
	buffer_load_dwordx4 v222, s[48:51], s6 offen lds
	s_add_i32 s6, s6, s62
	s_mov_b32 m0, s69
	s_nop 0
	buffer_load_dwordx4 v222, s[48:51], s6 offen lds
	s_add_i32 s6, s7, s63
	s_mov_b32 m0, s42
	s_nop 0
	buffer_load_dwordx4 v223, s[44:47], s6 offen lds
	s_add_i32 s6, s6, s63
	s_mov_b32 m0, s43
	s_nop 0
	buffer_load_dwordx4 v223, s[44:47], s6 offen lds
	s_waitcnt lgkmcnt(0)
	s_waitcnt vmcnt(8)
	s_barrier
	s_setprio 1
	v_mfma_f32_16x16x32_bf16 v[60:63], v[132:135], v[152:155], v[60:63]
	v_mfma_f32_16x16x32_bf16 v[56:59], v[140:143], v[152:155], v[56:59]
	v_mfma_f32_16x16x32_bf16 v[52:55], v[132:135], v[160:163], v[52:55]
	v_mfma_f32_16x16x32_bf16 v[48:51], v[140:143], v[160:163], v[48:51]
	v_mfma_f32_16x16x32_bf16 v[44:47], v[132:135], v[168:171], v[44:47]
	v_mfma_f32_16x16x32_bf16 v[40:43], v[140:143], v[168:171], v[40:43]
	v_mfma_f32_16x16x32_bf16 v[36:39], v[132:135], v[176:179], v[36:39]
	v_mfma_f32_16x16x32_bf16 v[32:35], v[140:143], v[176:179], v[32:35]
	v_mfma_f32_16x16x32_bf16 v[60:63], v[136:139], v[156:159], v[60:63]
	v_mfma_f32_16x16x32_bf16 v[56:59], v[144:147], v[156:159], v[56:59]
	v_mfma_f32_16x16x32_bf16 v[52:55], v[136:139], v[164:167], v[52:55]
	v_mfma_f32_16x16x32_bf16 v[48:51], v[144:147], v[164:167], v[48:51]
	v_mfma_f32_16x16x32_bf16 v[44:47], v[136:139], v[172:175], v[44:47]
	v_mfma_f32_16x16x32_bf16 v[40:43], v[144:147], v[172:175], v[40:43]
	v_mfma_f32_16x16x32_bf16 v[36:39], v[136:139], v[180:183], v[36:39]
	v_mfma_f32_16x16x32_bf16 v[32:35], v[144:147], v[180:183], v[32:35]
	v_mfma_f32_16x16x32_bf16 v[28:31], v[184:187], v[152:155], v[28:31]
	v_mfma_f32_16x16x32_bf16 v[24:27], v[192:195], v[152:155], v[24:27]
	v_mfma_f32_16x16x32_bf16 v[20:23], v[184:187], v[160:163], v[20:23]
	v_mfma_f32_16x16x32_bf16 v[16:19], v[192:195], v[160:163], v[16:19]
	v_mfma_f32_16x16x32_bf16 v[12:15], v[184:187], v[168:171], v[12:15]
	v_mfma_f32_16x16x32_bf16 v[8:11], v[192:195], v[168:171], v[8:11]
	v_mfma_f32_16x16x32_bf16 v[4:7], v[184:187], v[176:179], v[4:7]
	v_mfma_f32_16x16x32_bf16 v[0:3], v[192:195], v[176:179], v[0:3]
	v_mfma_f32_16x16x32_bf16 v[28:31], v[188:191], v[156:159], v[28:31]
	v_mfma_f32_16x16x32_bf16 v[24:27], v[196:199], v[156:159], v[24:27]
	v_mfma_f32_16x16x32_bf16 v[20:23], v[188:191], v[164:167], v[20:23]
	v_mfma_f32_16x16x32_bf16 v[16:19], v[196:199], v[164:167], v[16:19]
	v_mfma_f32_16x16x32_bf16 v[12:15], v[188:191], v[172:175], v[12:15]
	v_mfma_f32_16x16x32_bf16 v[8:11], v[196:199], v[172:175], v[8:11]
	v_mfma_f32_16x16x32_bf16 v[4:7], v[188:191], v[180:183], v[4:7]
	v_mfma_f32_16x16x32_bf16 v[0:3], v[196:199], v[180:183], v[0:3]
	s_setprio 0
	s_mov_b64 s[30:31], -1
	s_mov_b32 s8, 0
	s_branch .LBB0_318
